# de-serialised the 8 weight-row loads per iteration in loop LBB0_598 (issued together into v212-v243, counted vmcnt waits)
# speedup vs baseline: 1.0086x; 1.0086x over previous
.LBB0_598:
	v_lshl_add_u64 v[44:45], v[42:43], 0, s[44:45]
	global_load_dwordx4 v[212:215], v[44:45], off
	v_add_co_u32_e32 v244, vcc, s30, v44
	s_nop 1
	v_addc_co_u32_e32 v245, vcc, 0, v45, vcc
	global_load_dwordx4 v[216:219], v[244:245], off
	v_add_co_u32_e32 v244, vcc, 0x12000, v44
	s_nop 1
	v_addc_co_u32_e32 v245, vcc, 0, v45, vcc
	global_load_dwordx4 v[220:223], v[244:245], off
	v_add_co_u32_e32 v244, vcc, 0x1b000, v44
	s_nop 1
	v_addc_co_u32_e32 v245, vcc, 0, v45, vcc
	global_load_dwordx4 v[224:227], v[244:245], off
	v_add_co_u32_e32 v244, vcc, 0x24000, v44
	s_nop 1
	v_addc_co_u32_e32 v245, vcc, 0, v45, vcc
	global_load_dwordx4 v[228:231], v[244:245], off
	v_add_co_u32_e32 v244, vcc, 0x2d000, v44
	s_nop 1
	v_addc_co_u32_e32 v245, vcc, 0, v45, vcc
	global_load_dwordx4 v[232:235], v[244:245], off
	v_add_co_u32_e32 v244, vcc, 0x36000, v44
	s_nop 1
	v_addc_co_u32_e32 v245, vcc, 0, v45, vcc
	global_load_dwordx4 v[236:239], v[244:245], off
	v_add_co_u32_e32 v244, vcc, 0x3f000, v44
	s_nop 1
	v_addc_co_u32_e32 v245, vcc, 0, v45, vcc
	global_load_dwordx4 v[240:243], v[244:245], off
	ds_read_b128 v[46:49], v0
	ds_read_b128 v[2:5], v0 offset:16
	s_mov_b32 s20, 0x12000
	s_add_u32 s44, s44, 0x48000
	s_addc_u32 s45, s45, 0
	s_cmp_eq_u32 s44, 0x240000
	s_waitcnt vmcnt(7) lgkmcnt(1)
	v_mov_b64_e32 v[50:51], v[212:213]
	v_mov_b64_e32 v[52:53], v[214:215]
	v_pk_fma_f32 v[70:71], v[50:51], v[46:47], v[6:7] op_sel_hi:[1,0,1]
	v_pk_fma_f32 v[72:73], v[52:53], v[46:47], v[8:9] op_sel_hi:[1,0,1]
	ds_read_b128 v[6:9], v0 offset:4096
	s_waitcnt lgkmcnt(0)
	v_pk_fma_f32 v[74:75], v[50:51], v[6:7], v[14:15] op_sel_hi:[1,0,1]
	v_pk_fma_f32 v[76:77], v[52:53], v[6:7], v[16:17] op_sel_hi:[1,0,1]
	ds_read_b128 v[14:17], v0 offset:8192
	s_waitcnt lgkmcnt(0)
	v_pk_fma_f32 v[50:51], v[50:51], v[14:15], v[10:11] op_sel_hi:[1,0,1]
	v_add_co_u32_e32 v10, vcc, s30, v44
	v_pk_fma_f32 v[52:53], v[52:53], v[14:15], v[12:13] op_sel_hi:[1,0,1]
	s_nop 0
	v_addc_co_u32_e32 v11, vcc, 0, v45, vcc
	s_waitcnt vmcnt(6)
	v_mov_b64_e32 v[10:11], v[216:217]
	v_mov_b64_e32 v[12:13], v[218:219]
	v_pk_fma_f32 v[70:71], v[10:11], v[46:47], v[70:71] op_sel:[0,1,0]
	v_pk_fma_f32 v[46:47], v[12:13], v[46:47], v[72:73] op_sel:[0,1,0]
	v_pk_fma_f32 v[72:73], v[10:11], v[6:7], v[74:75] op_sel:[0,1,0]
	v_pk_fma_f32 v[50:51], v[10:11], v[14:15], v[50:51] op_sel:[0,1,0]
	v_add_co_u32_e32 v10, vcc, s20, v44
	v_pk_fma_f32 v[6:7], v[12:13], v[6:7], v[76:77] op_sel:[0,1,0]
	s_nop 0
	v_addc_co_u32_e32 v11, vcc, 0, v45, vcc
	v_pk_fma_f32 v[14:15], v[12:13], v[14:15], v[52:53] op_sel:[0,1,0]
	s_mov_b32 s20, 0x1b000
	s_waitcnt vmcnt(5)
	v_mov_b64_e32 v[10:11], v[220:221]
	v_mov_b64_e32 v[12:13], v[222:223]
	v_pk_fma_f32 v[52:53], v[10:11], v[48:49], v[70:71] op_sel_hi:[1,0,1]
	v_pk_fma_f32 v[70:71], v[10:11], v[8:9], v[72:73] op_sel_hi:[1,0,1]
	v_pk_fma_f32 v[50:51], v[10:11], v[16:17], v[50:51] op_sel_hi:[1,0,1]
	v_add_co_u32_e32 v10, vcc, s20, v44
	v_pk_fma_f32 v[46:47], v[12:13], v[48:49], v[46:47] op_sel_hi:[1,0,1]
	s_nop 0
	v_addc_co_u32_e32 v11, vcc, 0, v45, vcc
	v_pk_fma_f32 v[6:7], v[12:13], v[8:9], v[6:7] op_sel_hi:[1,0,1]
	v_pk_fma_f32 v[14:15], v[12:13], v[16:17], v[14:15] op_sel_hi:[1,0,1]
	v_mov_b32_e32 v8, v49
	s_mov_b32 s20, 0x24000
	s_waitcnt vmcnt(4)
	v_mov_b64_e32 v[10:11], v[224:225]
	v_mov_b64_e32 v[12:13], v[226:227]
	v_pk_fma_f32 v[48:49], v[10:11], v[8:9], v[52:53] op_sel_hi:[1,0,1]
	v_pk_fma_f32 v[46:47], v[12:13], v[8:9], v[46:47] op_sel_hi:[1,0,1]
	v_mov_b32_e32 v8, v9
	v_pk_fma_f32 v[52:53], v[10:11], v[8:9], v[70:71] op_sel_hi:[1,0,1]
	v_pk_fma_f32 v[70:71], v[12:13], v[8:9], v[6:7] op_sel_hi:[1,0,1]
	v_mov_b32_e32 v6, v17
	v_pk_fma_f32 v[16:17], v[10:11], v[6:7], v[50:51] op_sel_hi:[1,0,1]
	v_pk_fma_f32 v[14:15], v[12:13], v[6:7], v[14:15] op_sel_hi:[1,0,1]
	v_add_co_u32_e32 v6, vcc, s20, v44
	ds_read_b128 v[10:13], v0 offset:4112
	s_nop 0
	v_addc_co_u32_e32 v7, vcc, 0, v45, vcc
	s_mov_b32 s20, 0x2d000
	s_waitcnt vmcnt(3)
	v_mov_b64_e32 v[6:7], v[228:229]
	v_mov_b64_e32 v[8:9], v[230:231]
	v_pk_fma_f32 v[50:51], v[6:7], v[2:3], v[48:49] op_sel_hi:[1,0,1]
	v_pk_fma_f32 v[72:73], v[8:9], v[2:3], v[46:47] op_sel_hi:[1,0,1]
	ds_read_b128 v[46:49], v0 offset:8208
	s_waitcnt lgkmcnt(1)
	v_pk_fma_f32 v[52:53], v[6:7], v[10:11], v[52:53] op_sel_hi:[1,0,1]
	v_pk_fma_f32 v[70:71], v[8:9], v[10:11], v[70:71] op_sel_hi:[1,0,1]
	v_add_u32_e32 v0, 32, v0
	s_waitcnt lgkmcnt(0)
	v_pk_fma_f32 v[16:17], v[6:7], v[46:47], v[16:17] op_sel_hi:[1,0,1]
	v_add_co_u32_e32 v6, vcc, s20, v44
	v_pk_fma_f32 v[14:15], v[8:9], v[46:47], v[14:15] op_sel_hi:[1,0,1]
	s_nop 0
	v_addc_co_u32_e32 v7, vcc, 0, v45, vcc
	s_mov_b32 s20, 0x36000
	s_waitcnt vmcnt(2)
	v_mov_b64_e32 v[6:7], v[232:233]
	v_mov_b64_e32 v[8:9], v[234:235]
	v_pk_fma_f32 v[50:51], v[6:7], v[2:3], v[50:51] op_sel:[0,1,0]
	v_pk_fma_f32 v[52:53], v[6:7], v[10:11], v[52:53] op_sel:[0,1,0]
	v_pk_fma_f32 v[16:17], v[6:7], v[46:47], v[16:17] op_sel:[0,1,0]
	v_add_co_u32_e32 v6, vcc, s20, v44
	v_pk_fma_f32 v[2:3], v[8:9], v[2:3], v[72:73] op_sel:[0,1,0]
	s_nop 0
	v_addc_co_u32_e32 v7, vcc, 0, v45, vcc
	v_pk_fma_f32 v[10:11], v[8:9], v[10:11], v[70:71] op_sel:[0,1,0]
	v_pk_fma_f32 v[14:15], v[8:9], v[46:47], v[14:15] op_sel:[0,1,0]
	s_mov_b32 s20, 0x3f000
	s_waitcnt vmcnt(1)
	v_mov_b64_e32 v[6:7], v[236:237]
	v_mov_b64_e32 v[8:9], v[238:239]
	v_pk_fma_f32 v[50:51], v[6:7], v[4:5], v[50:51] op_sel_hi:[1,0,1]
	v_pk_fma_f32 v[52:53], v[6:7], v[12:13], v[52:53] op_sel_hi:[1,0,1]
	v_pk_fma_f32 v[70:71], v[6:7], v[48:49], v[16:17] op_sel_hi:[1,0,1]
	v_add_co_u32_e32 v6, vcc, s20, v44
	v_pk_fma_f32 v[2:3], v[8:9], v[4:5], v[2:3] op_sel_hi:[1,0,1]
	s_nop 0
	v_addc_co_u32_e32 v7, vcc, 0, v45, vcc
	v_mov_b32_e32 v4, v5
	v_pk_fma_f32 v[10:11], v[8:9], v[12:13], v[10:11] op_sel_hi:[1,0,1]
	v_pk_fma_f32 v[72:73], v[8:9], v[48:49], v[14:15] op_sel_hi:[1,0,1]
	s_waitcnt vmcnt(0)
	v_mov_b64_e32 v[44:45], v[240:241]
	v_mov_b64_e32 v[46:47], v[242:243]
	v_pk_fma_f32 v[8:9], v[46:47], v[4:5], v[2:3] op_sel_hi:[1,0,1]
	v_mov_b32_e32 v2, v13
	v_pk_fma_f32 v[14:15], v[44:45], v[2:3], v[52:53] op_sel_hi:[1,0,1]
	v_pk_fma_f32 v[16:17], v[46:47], v[2:3], v[10:11] op_sel_hi:[1,0,1]
	v_mov_b32_e32 v2, v49
	v_pk_fma_f32 v[6:7], v[44:45], v[4:5], v[50:51] op_sel_hi:[1,0,1]
	v_pk_fma_f32 v[10:11], v[44:45], v[2:3], v[70:71] op_sel_hi:[1,0,1]
	v_pk_fma_f32 v[12:13], v[46:47], v[2:3], v[72:73] op_sel_hi:[1,0,1]
	s_cbranch_scc0 .LBB0_598
	ds_write_b128 v56, v[6:9] offset:12288
	ds_write_b128 v56, v[14:17] offset:12544
	ds_write_b128 v56, v[10:13] offset:12800
	s_waitcnt lgkmcnt(0)
	s_barrier
	s_and_saveexec_b64 s[20:21], s[36:37]
	s_cbranch_execz .LBB0_516
	v_lshlrev_b32_e32 v2, 6, v69
	v_or_b32_e32 v4, v2, v20
	v_readlane_b32 s4, v254, 25
	v_ashrrev_i32_e32 v5, 31, v4
	v_readlane_b32 s6, v254, 27
	v_readlane_b32 s7, v254, 28
	v_ashrrev_i32_e32 v3, 31, v2
	v_lshl_add_u64 v[2:3], v[2:3], 2, v[24:25]
	v_lshl_add_u64 v[4:5], v[4:5], 2, s[6:7]
	global_load_dword v0, v[4:5], off
	ds_read2st64_b32 v[4:5], v59 offset0:48 offset1:60
	ds_read2st64_b32 v[6:7], v57 offset0:51 offset1:54
	ds_read2st64_b32 v[8:9], v57 offset0:57 offset1:63
	ds_read2st64_b32 v[10:11], v57 offset0:66 offset1:69
	ds_read2st64_b32 v[12:13], v59 offset0:72 offset1:84
	ds_read2st64_b32 v[14:15], v57 offset0:75 offset1:78
	ds_read2st64_b32 v[16:17], v57 offset0:81 offset1:87
	ds_read2st64_b32 v[42:43], v57 offset0:90 offset1:93
	v_readlane_b32 s5, v254, 26
	v_readlane_b32 s8, v254, 29
	v_readlane_b32 s9, v254, 30
	v_readlane_b32 s10, v254, 31
	v_readlane_b32 s11, v254, 32
	v_readlane_b32 s12, v254, 33
	v_readlane_b32 s13, v254, 34
	v_readlane_b32 s14, v254, 35
	v_readlane_b32 s15, v254, 36
	v_readlane_b32 s16, v254, 37
	v_readlane_b32 s17, v254, 38
	v_readlane_b32 s18, v254, 39
	v_readlane_b32 s19, v254, 40
	s_waitcnt vmcnt(0) lgkmcnt(7)
	v_add_f32_e32 v0, v0, v4
	s_waitcnt lgkmcnt(6)
	v_add_f32_e32 v0, v0, v6
	v_add_f32_e32 v0, v0, v7
	s_waitcnt lgkmcnt(5)
	v_add_f32_e32 v0, v0, v8
	v_add_f32_e32 v0, v0, v5
	v_add_f32_e32 v0, v0, v9
	s_waitcnt lgkmcnt(4)
	v_add_f32_e32 v0, v0, v10
	v_add_f32_e32 v0, v0, v11
	s_waitcnt lgkmcnt(3)
	v_add_f32_e32 v0, v0, v12
	s_waitcnt lgkmcnt(2)
	v_add_f32_e32 v0, v0, v14
	v_add_f32_e32 v0, v0, v15
	s_waitcnt lgkmcnt(1)
	v_add_f32_e32 v0, v0, v16
	v_add_f32_e32 v0, v0, v13
	v_add_f32_e32 v0, v0, v17
	s_waitcnt lgkmcnt(0)
	v_add_f32_e32 v0, v0, v42
	v_add_f32_e32 v0, v0, v43
	global_store_dword v[2:3], v0, off
	s_branch .LBB0_516
